# v4_epi_pipe
# speedup vs baseline: 1.0025x; 1.0025x over previous
;     __device__ __forceinline__ void operator()(const f32x4 (&acc)[2][2][4][2], const Unit& u, int wr, int wc, int fr, int fq, int lane) const {
;         const int row0 = u.row0 + wr * 64 + fr, col0 = u.col0 + wc * 32 + 8 * fq;
;         const int b = tok_batch(u.row0);
;         const float* xin = (u.row0 < TP) ? xp : xs;
;         f32x4 g[2][2];
; #pragma unroll
;         for (int bj = 0; bj < 2; ++bj)
; #pragma unroll
;             for (int n = 0; n < 2; ++n) g[bj][n] = *(const f32x4*)(gate + b * 12288 + col0 + bj * HALF + n * 4);
; #pragma unroll
;         for (int ai = 0; ai < 2; ++ai)
; #pragma unroll
;             for (int m = 0; m < 4; ++m) { const size_t ro = (size_t)(row0 + ai * HALF + m * 16) * D + col0;
;                 f32x4 xo[2][2];
; #pragma unroll
;                 for (int bj = 0; bj < 2; ++bj)
; #pragma unroll
;                     for (int n = 0; n < 2; ++n) xo[bj][n] = *(const f32x4*)(xin + ro + bj * HALF + n * 4);
; #pragma unroll
;                 for (int bj = 0; bj < 2; ++bj)
; #pragma unroll
;                     for (int n = 0; n < 2; ++n) *(f32x4*)(out + ro + bj * HALF + n * 4) = xo[bj][n] + g[bj][n] * acc[ai][bj][m][n]; }
.LBB0_110:
	s_add_i32 s13, s48, 0xffffc000
	s_lshr_b32 s13, s13, 12
	s_ashr_i32 s12, s48, 13
	s_add_i32 s13, s13, 2
	s_cmpk_lt_i32 s48, 0x4000
	s_cselect_b32 s22, s12, s13
	s_mulk_i32 s22, 0x3000
	s_cselect_b32 s13, s28, s30
	s_cselect_b32 s12, s29, s31
	s_ashr_i32 s23, s22, 31
	s_lshl_b64 s[22:23], s[22:23], 2
	v_add_u32_e32 v164, s48, v1
	v_add_u32_e32 v158, s49, v161
	s_add_u32 s22, s34, s22
	v_ashrrev_i32_e32 v165, 31, v164
	s_addc_u32 s23, s35, s23
	v_ashrrev_i32_e32 v159, 31, v158
	v_lshlrev_b64 v[164:165], 11, v[164:165]
	v_lshl_add_u64 v[90:91], v[158:159], 2, s[22:23]
	v_lshl_add_u64 v[158:159], v[164:165], 0, v[158:159]
	v_lshlrev_b64 v[158:159], 2, v[158:159]
	v_lshl_add_u64 v[176:177], s[12:13], 0, v[158:159]
	global_load_dwordx4 v[86:89], v[90:91], off offset:16
	global_load_dwordx4 v[94:97], v[90:91], off
	global_load_dwordx4 v[82:85], v[90:91], off offset:528
	s_nop 0
	global_load_dwordx4 v[90:93], v[90:91], off offset:512
	s_nop 0
	global_load_dwordx4 v[168:171], v[176:177], off offset:16
	global_load_dwordx4 v[172:175], v[176:177], off offset:512
	global_load_dwordx4 v[196:199], v[176:177], off offset:528
	global_load_dwordx4 v[164:167], v[176:177], off
	s_mov_b64 s[22:23], 0x20000
	v_lshl_add_u64 v[200:201], v[176:177], 0, s[22:23]
	global_load_dwordx4 v[204:207], v[200:201], off offset:16
	global_load_dwordx4 v[208:211], v[200:201], off offset:512
	global_load_dwordx4 v[212:215], v[200:201], off offset:528
	global_load_dwordx4 v[200:203], v[200:201], off
	s_mov_b64 s[22:23], 0x40000
	v_lshl_add_u64 v[224:225], v[176:177], 0, s[22:23]
	global_load_dwordx4 v[228:231], v[224:225], off offset:16
	global_load_dwordx4 v[232:235], v[224:225], off offset:512
	global_load_dwordx4 v[236:239], v[224:225], off offset:528
	global_load_dwordx4 v[224:227], v[224:225], off
	v_readlane_b32 s56, v254, 44
	v_readlane_b32 s70, v254, 58
	v_readlane_b32 s71, v254, 59
	s_andn2_b64 vcc, exec, s[0:1]
	v_readlane_b32 s57, v254, 45
	v_readlane_b32 s58, v254, 46
	v_readlane_b32 s59, v254, 47
	v_readlane_b32 s60, v254, 48
	v_readlane_b32 s61, v254, 49
	v_readlane_b32 s62, v254, 50
	v_readlane_b32 s63, v254, 51
	v_readlane_b32 s64, v254, 52
	v_readlane_b32 s65, v254, 53
	v_readlane_b32 s66, v254, 54
	v_readlane_b32 s67, v254, 55
	v_readlane_b32 s68, v254, 56
	v_readlane_b32 s69, v254, 57
	v_lshl_add_u64 v[158:159], s[70:71], 0, v[158:159]
	s_waitcnt vmcnt(8)
	v_pk_fma_f32 v[142:143], v[142:143], v[94:95], v[164:165]
	v_pk_fma_f32 v[144:145], v[144:145], v[96:97], v[166:167]
	v_pk_fma_f32 v[138:139], v[138:139], v[86:87], v[168:169]
	v_pk_fma_f32 v[140:141], v[140:141], v[88:89], v[170:171]
	v_pk_fma_f32 v[134:135], v[134:135], v[90:91], v[172:173]
	v_pk_fma_f32 v[136:137], v[136:137], v[92:93], v[174:175]
	v_pk_fma_f32 v[130:131], v[130:131], v[82:83], v[196:197]
	v_pk_fma_f32 v[132:133], v[132:133], v[84:85], v[198:199]
	global_store_dwordx4 v[158:159], v[142:145], off
	global_store_dwordx4 v[158:159], v[138:141], off offset:16
	global_store_dwordx4 v[158:159], v[134:137], off offset:512
	global_store_dwordx4 v[158:159], v[130:133], off offset:528
	s_mov_b64 s[22:23], 0x60000
	v_lshl_add_u64 v[164:165], v[176:177], 0, s[22:23]
	global_load_dwordx4 v[168:171], v[164:165], off offset:16
	global_load_dwordx4 v[172:175], v[164:165], off offset:512
	global_load_dwordx4 v[196:199], v[164:165], off offset:528
	global_load_dwordx4 v[164:167], v[164:165], off
	s_waitcnt vmcnt(12)
	v_pk_fma_f32 v[126:127], v[126:127], v[94:95], v[200:201]
	v_pk_fma_f32 v[128:129], v[128:129], v[96:97], v[202:203]
	v_pk_fma_f32 v[122:123], v[122:123], v[86:87], v[204:205]
	v_pk_fma_f32 v[124:125], v[124:125], v[88:89], v[206:207]
	v_pk_fma_f32 v[118:119], v[118:119], v[90:91], v[208:209]
	v_pk_fma_f32 v[120:121], v[120:121], v[92:93], v[210:211]
	v_pk_fma_f32 v[114:115], v[114:115], v[82:83], v[212:213]
	v_pk_fma_f32 v[116:117], v[116:117], v[84:85], v[214:215]
	s_mov_b64 s[22:23], 0x20000
	v_lshl_add_u64 v[200:201], v[158:159], 0, s[22:23]
	global_store_dwordx4 v[200:201], v[126:129], off
	global_store_dwordx4 v[200:201], v[122:125], off offset:16
	global_store_dwordx4 v[200:201], v[118:121], off offset:512
	global_store_dwordx4 v[200:201], v[114:117], off offset:528
	s_mov_b64 s[22:23], 0x100000
	v_lshl_add_u64 v[200:201], v[176:177], 0, s[22:23]
	global_load_dwordx4 v[204:207], v[200:201], off offset:16
	global_load_dwordx4 v[208:211], v[200:201], off offset:512
	global_load_dwordx4 v[212:215], v[200:201], off offset:528
	global_load_dwordx4 v[200:203], v[200:201], off
	s_waitcnt vmcnt(16)
	v_pk_fma_f32 v[110:111], v[110:111], v[94:95], v[224:225]
	v_pk_fma_f32 v[112:113], v[112:113], v[96:97], v[226:227]
	v_pk_fma_f32 v[106:107], v[106:107], v[86:87], v[228:229]
	v_pk_fma_f32 v[108:109], v[108:109], v[88:89], v[230:231]
	v_pk_fma_f32 v[102:103], v[102:103], v[90:91], v[232:233]
	v_pk_fma_f32 v[104:105], v[104:105], v[92:93], v[234:235]
	v_pk_fma_f32 v[98:99], v[98:99], v[82:83], v[236:237]
	v_pk_fma_f32 v[100:101], v[100:101], v[84:85], v[238:239]
	s_mov_b64 s[22:23], 0x40000
	v_lshl_add_u64 v[224:225], v[158:159], 0, s[22:23]
	global_store_dwordx4 v[224:225], v[110:113], off
	global_store_dwordx4 v[224:225], v[106:109], off offset:16
	global_store_dwordx4 v[224:225], v[102:105], off offset:512
	global_store_dwordx4 v[224:225], v[98:101], off offset:528
	s_mov_b64 s[22:23], 0x120000
	v_lshl_add_u64 v[224:225], v[176:177], 0, s[22:23]
	global_load_dwordx4 v[228:231], v[224:225], off offset:16
	global_load_dwordx4 v[232:235], v[224:225], off offset:512
	global_load_dwordx4 v[236:239], v[224:225], off offset:528
	global_load_dwordx4 v[224:227], v[224:225], off
	s_waitcnt vmcnt(16)
;     __device__ __forceinline__ void operator()(const f32x4 (&acc)[2][2][4][2], const Unit& u, int wr, int wc, int fr, int fq, int lane) const {
;     ...
;             for (int m = 0; m < 4; ++m) { const size_t ro = (size_t)(row0 + ai * HALF + m * 16) * D + col0;
;                 f32x4 xo[2][2];
; #pragma unroll
;                 for (int bj = 0; bj < 2; ++bj)
; #pragma unroll
;                     for (int n = 0; n < 2; ++n) xo[bj][n] = *(const f32x4*)(xin + ro + bj * HALF + n * 4);
; #pragma unroll
;                 for (int bj = 0; bj < 2; ++bj)
; #pragma unroll
;                     for (int n = 0; n < 2; ++n) *(f32x4*)(out + ro + bj * HALF + n * 4) = xo[bj][n] + g[bj][n] * acc[ai][bj][m][n]; }
	v_pk_fma_f32 v[78:79], v[78:79], v[94:95], v[164:165]
	v_pk_fma_f32 v[80:81], v[80:81], v[96:97], v[166:167]
	v_pk_fma_f32 v[74:75], v[74:75], v[86:87], v[168:169]
	v_pk_fma_f32 v[76:77], v[76:77], v[88:89], v[170:171]
	v_pk_fma_f32 v[70:71], v[70:71], v[90:91], v[172:173]
	v_pk_fma_f32 v[72:73], v[72:73], v[92:93], v[174:175]
	v_pk_fma_f32 v[66:67], v[66:67], v[82:83], v[196:197]
	v_pk_fma_f32 v[68:69], v[68:69], v[84:85], v[198:199]
	s_mov_b64 s[22:23], 0x60000
	v_lshl_add_u64 v[164:165], v[158:159], 0, s[22:23]
	global_store_dwordx4 v[164:165], v[78:81], off
	global_store_dwordx4 v[164:165], v[74:77], off offset:16
	global_store_dwordx4 v[164:165], v[70:73], off offset:512
	global_store_dwordx4 v[164:165], v[66:69], off offset:528
	s_mov_b64 s[22:23], 0x140000
	v_lshl_add_u64 v[164:165], v[176:177], 0, s[22:23]
	global_load_dwordx4 v[168:171], v[164:165], off offset:16
	global_load_dwordx4 v[172:175], v[164:165], off offset:512
	global_load_dwordx4 v[196:199], v[164:165], off offset:528
	global_load_dwordx4 v[164:167], v[164:165], off
	s_waitcnt vmcnt(16)
	v_pk_fma_f32 v[62:63], v[62:63], v[94:95], v[200:201]
	v_pk_fma_f32 v[64:65], v[64:65], v[96:97], v[202:203]
	v_pk_fma_f32 v[58:59], v[58:59], v[86:87], v[204:205]
	v_pk_fma_f32 v[60:61], v[60:61], v[88:89], v[206:207]
	v_pk_fma_f32 v[54:55], v[54:55], v[90:91], v[208:209]
	v_pk_fma_f32 v[56:57], v[56:57], v[92:93], v[210:211]
	v_pk_fma_f32 v[50:51], v[50:51], v[82:83], v[212:213]
	v_pk_fma_f32 v[52:53], v[52:53], v[84:85], v[214:215]
	s_mov_b64 s[22:23], 0x100000
	v_lshl_add_u64 v[200:201], v[158:159], 0, s[22:23]
	global_store_dwordx4 v[200:201], v[62:65], off
	global_store_dwordx4 v[200:201], v[58:61], off offset:16
	global_store_dwordx4 v[200:201], v[54:57], off offset:512
	global_store_dwordx4 v[200:201], v[50:53], off offset:528
	s_mov_b64 s[22:23], 0x160000
	v_lshl_add_u64 v[200:201], v[176:177], 0, s[22:23]
	global_load_dwordx4 v[204:207], v[200:201], off offset:16
	global_load_dwordx4 v[208:211], v[200:201], off offset:512
	global_load_dwordx4 v[212:215], v[200:201], off offset:528
	global_load_dwordx4 v[200:203], v[200:201], off
	s_waitcnt vmcnt(16)
	v_pk_fma_f32 v[46:47], v[46:47], v[94:95], v[224:225]
	v_pk_fma_f32 v[48:49], v[48:49], v[96:97], v[226:227]
	v_pk_fma_f32 v[42:43], v[42:43], v[86:87], v[228:229]
	v_pk_fma_f32 v[44:45], v[44:45], v[88:89], v[230:231]
	v_pk_fma_f32 v[38:39], v[38:39], v[90:91], v[232:233]
	v_pk_fma_f32 v[40:41], v[40:41], v[92:93], v[234:235]
	v_pk_fma_f32 v[34:35], v[34:35], v[82:83], v[236:237]
	v_pk_fma_f32 v[36:37], v[36:37], v[84:85], v[238:239]
	s_mov_b64 s[22:23], 0x120000
	v_lshl_add_u64 v[224:225], v[158:159], 0, s[22:23]
	global_store_dwordx4 v[224:225], v[46:49], off
	global_store_dwordx4 v[224:225], v[42:45], off offset:16
	global_store_dwordx4 v[224:225], v[38:41], off offset:512
	global_store_dwordx4 v[224:225], v[34:37], off offset:528
	s_waitcnt vmcnt(12)
	v_pk_fma_f32 v[30:31], v[30:31], v[94:95], v[164:165]
	v_pk_fma_f32 v[32:33], v[32:33], v[96:97], v[166:167]
	v_pk_fma_f32 v[26:27], v[26:27], v[86:87], v[168:169]
	v_pk_fma_f32 v[28:29], v[28:29], v[88:89], v[170:171]
	v_pk_fma_f32 v[22:23], v[22:23], v[90:91], v[172:173]
	v_pk_fma_f32 v[24:25], v[24:25], v[92:93], v[174:175]
	v_pk_fma_f32 v[18:19], v[18:19], v[82:83], v[196:197]
	v_pk_fma_f32 v[20:21], v[20:21], v[84:85], v[198:199]
	s_mov_b64 s[22:23], 0x140000
	v_lshl_add_u64 v[164:165], v[158:159], 0, s[22:23]
	global_store_dwordx4 v[164:165], v[30:33], off
	global_store_dwordx4 v[164:165], v[26:29], off offset:16
	global_store_dwordx4 v[164:165], v[22:25], off offset:512
	global_store_dwordx4 v[164:165], v[18:21], off offset:528
	s_waitcnt vmcnt(8)
	v_pk_fma_f32 v[14:15], v[14:15], v[94:95], v[200:201]
	v_pk_fma_f32 v[16:17], v[16:17], v[96:97], v[202:203]
	v_pk_fma_f32 v[10:11], v[10:11], v[86:87], v[204:205]
	v_pk_fma_f32 v[12:13], v[12:13], v[88:89], v[206:207]
	v_pk_fma_f32 v[6:7], v[6:7], v[90:91], v[208:209]
	v_pk_fma_f32 v[8:9], v[8:9], v[92:93], v[210:211]
	v_pk_fma_f32 v[2:3], v[2:3], v[82:83], v[212:213]
	v_pk_fma_f32 v[4:5], v[4:5], v[84:85], v[214:215]
	s_mov_b64 s[22:23], 0x160000
	v_lshl_add_u64 v[200:201], v[158:159], 0, s[22:23]
	global_store_dwordx4 v[200:201], v[14:17], off
	global_store_dwordx4 v[200:201], v[10:13], off offset:16
	global_store_dwordx4 v[200:201], v[6:9], off offset:512
	global_store_dwordx4 v[200:201], v[2:5], off offset:528
	s_mov_b64 s[12:13], -1
	s_cbranch_vccnz .LBB0_99
	s_andn2_b64 vcc, exec, s[4:5]
	s_cbranch_vccnz .LBB0_98
	s_barrier
	s_branch .LBB0_98

;     __device__ __forceinline__ void operator()(const f32x4 (&acc)[2][2][4][2], const Unit& u, int wr, int wc, int fr, int fq, int lane) const {
;         const int row0 = u.row0 + wr * 64 + fr, col0 = u.col0 + wc * 32 + 8 * fq;
;         const int b = tok_batch(u.row0);
;         const float* xin = (u.row0 < TP) ? xp : xs;
;         f32x4 g[2][2];
; #pragma unroll
;         for (int bj = 0; bj < 2; ++bj)
; #pragma unroll
;             for (int n = 0; n < 2; ++n) g[bj][n] = *(const f32x4*)(gate + b * 12288 + col0 + bj * HALF + n * 4);
; #pragma unroll
;         for (int ai = 0; ai < 2; ++ai)
; #pragma unroll
;             for (int m = 0; m < 4; ++m) { const size_t ro = (size_t)(row0 + ai * HALF + m * 16) * D + col0;
;                 f32x4 xo[2][2];
; #pragma unroll
;                 for (int bj = 0; bj < 2; ++bj)
; #pragma unroll
;                     for (int n = 0; n < 2; ++n) xo[bj][n] = *(const f32x4*)(xin + ro + bj * HALF + n * 4);
; #pragma unroll
;                 for (int bj = 0; bj < 2; ++bj)
; #pragma unroll
;                     for (int n = 0; n < 2; ++n) *(f32x4*)(out + ro + bj * HALF + n * 4) = xo[bj][n] + g[bj][n] * acc[ai][bj][m][n]; }
.LBB0_358:
	s_add_i32 s13, s40, 0xffffc000
	s_lshr_b32 s13, s13, 12
	s_ashr_i32 s12, s40, 13
	s_add_i32 s13, s13, 2
	s_cmpk_lt_i32 s40, 0x4000
	s_cselect_b32 s12, s12, s13
	s_mulk_i32 s12, 0x3000
	s_ashr_i32 s13, s12, 31
	v_add_u32_e32 v164, s40, v1
	v_add_u32_e32 v50, s41, v161
	s_lshl_b64 s[12:13], s[12:13], 2
	v_ashrrev_i32_e32 v165, 31, v164
	v_readlane_b32 s56, v254, 44
	s_add_u32 s12, s28, s12
	v_ashrrev_i32_e32 v51, 31, v50
	v_lshlrev_b64 v[164:165], 13, v[164:165]
	v_readlane_b32 s70, v254, 58
	v_readlane_b32 s71, v254, 59
	s_addc_u32 s13, s29, s13
	v_lshlrev_b64 v[158:159], 2, v[50:51]
	v_lshl_add_u64 v[164:165], s[70:71], 0, v[164:165]
	v_lshl_add_u64 v[54:55], s[12:13], 0, v[158:159]
	v_lshl_add_u64 v[158:159], v[164:165], 0, v[158:159]
	global_load_dwordx4 v[58:61], v[54:55], off offset:16
	global_load_dwordx4 v[62:65], v[54:55], off
	global_load_dwordx4 v[50:53], v[54:55], off offset:528
	s_nop 0
	global_load_dwordx4 v[54:57], v[54:55], off offset:512
	s_nop 0
	global_load_dwordx4 v[168:171], v[158:159], off offset:16
	global_load_dwordx4 v[172:175], v[158:159], off offset:512
	global_load_dwordx4 v[196:199], v[158:159], off offset:528
	global_load_dwordx4 v[164:167], v[158:159], off
	s_mov_b64 s[12:13], 0x20000
	v_lshl_add_u64 v[200:201], v[158:159], 0, s[12:13]
	global_load_dwordx4 v[204:207], v[200:201], off offset:16
	global_load_dwordx4 v[208:211], v[200:201], off offset:512
	global_load_dwordx4 v[212:215], v[200:201], off offset:528
	global_load_dwordx4 v[200:203], v[200:201], off
	s_mov_b64 s[12:13], 0x40000
	v_lshl_add_u64 v[224:225], v[158:159], 0, s[12:13]
	global_load_dwordx4 v[228:231], v[224:225], off offset:16
	global_load_dwordx4 v[232:235], v[224:225], off offset:512
	global_load_dwordx4 v[236:239], v[224:225], off offset:528
	global_load_dwordx4 v[224:227], v[224:225], off
	v_readlane_b32 s57, v254, 45
	v_readlane_b32 s58, v254, 46
	v_readlane_b32 s59, v254, 47
	v_readlane_b32 s60, v254, 48
	v_readlane_b32 s61, v254, 49
	v_readlane_b32 s62, v254, 50
	v_readlane_b32 s63, v254, 51
	v_readlane_b32 s64, v254, 52
	v_readlane_b32 s65, v254, 53
	v_readlane_b32 s66, v254, 54
	v_readlane_b32 s67, v254, 55
	v_readlane_b32 s68, v254, 56
	v_readlane_b32 s69, v254, 57
	s_waitcnt vmcnt(8)
	v_pk_fma_f32 v[142:143], v[142:143], v[62:63], v[164:165]
	v_pk_fma_f32 v[144:145], v[144:145], v[64:65], v[166:167]
	v_pk_fma_f32 v[138:139], v[138:139], v[58:59], v[168:169]
	v_pk_fma_f32 v[140:141], v[140:141], v[60:61], v[170:171]
	v_pk_fma_f32 v[134:135], v[134:135], v[54:55], v[172:173]
	v_pk_fma_f32 v[136:137], v[136:137], v[56:57], v[174:175]
	v_pk_fma_f32 v[130:131], v[130:131], v[50:51], v[196:197]
	v_pk_fma_f32 v[132:133], v[132:133], v[52:53], v[198:199]
	global_store_dwordx4 v[158:159], v[142:145], off
	global_store_dwordx4 v[158:159], v[138:141], off offset:16
	global_store_dwordx4 v[158:159], v[134:137], off offset:512
	global_store_dwordx4 v[158:159], v[130:133], off offset:528
	s_mov_b64 s[12:13], 0x60000
	v_lshl_add_u64 v[164:165], v[158:159], 0, s[12:13]
	global_load_dwordx4 v[168:171], v[164:165], off offset:16
	global_load_dwordx4 v[172:175], v[164:165], off offset:512
	global_load_dwordx4 v[196:199], v[164:165], off offset:528
	global_load_dwordx4 v[164:167], v[164:165], off
	s_waitcnt vmcnt(12)
	v_pk_fma_f32 v[126:127], v[126:127], v[62:63], v[200:201]
	v_pk_fma_f32 v[128:129], v[128:129], v[64:65], v[202:203]
	v_pk_fma_f32 v[122:123], v[122:123], v[58:59], v[204:205]
	v_pk_fma_f32 v[124:125], v[124:125], v[60:61], v[206:207]
	v_pk_fma_f32 v[110:111], v[110:111], v[54:55], v[208:209]
	v_pk_fma_f32 v[112:113], v[112:113], v[56:57], v[210:211]
	v_pk_fma_f32 v[106:107], v[106:107], v[50:51], v[212:213]
	v_pk_fma_f32 v[108:109], v[108:109], v[52:53], v[214:215]
	s_mov_b64 s[12:13], 0x20000
	v_lshl_add_u64 v[200:201], v[158:159], 0, s[12:13]
	global_store_dwordx4 v[200:201], v[126:129], off
	global_store_dwordx4 v[200:201], v[122:125], off offset:16
	global_store_dwordx4 v[200:201], v[110:113], off offset:512
	global_store_dwordx4 v[200:201], v[106:109], off offset:528
	s_mov_b64 s[12:13], 0x100000
	v_lshl_add_u64 v[200:201], v[158:159], 0, s[12:13]
	global_load_dwordx4 v[204:207], v[200:201], off offset:16
	global_load_dwordx4 v[208:211], v[200:201], off offset:512
	global_load_dwordx4 v[212:215], v[200:201], off offset:528
	global_load_dwordx4 v[200:203], v[200:201], off
	s_waitcnt vmcnt(16)
	v_pk_fma_f32 v[118:119], v[118:119], v[62:63], v[224:225]
	v_pk_fma_f32 v[120:121], v[120:121], v[64:65], v[226:227]
	v_pk_fma_f32 v[114:115], v[114:115], v[58:59], v[228:229]
	v_pk_fma_f32 v[116:117], v[116:117], v[60:61], v[230:231]
	v_pk_fma_f32 v[102:103], v[102:103], v[54:55], v[232:233]
	v_pk_fma_f32 v[104:105], v[104:105], v[56:57], v[234:235]
	v_pk_fma_f32 v[98:99], v[98:99], v[50:51], v[236:237]
	v_pk_fma_f32 v[100:101], v[100:101], v[52:53], v[238:239]
	s_mov_b64 s[12:13], 0x40000
	v_lshl_add_u64 v[224:225], v[158:159], 0, s[12:13]
	global_store_dwordx4 v[224:225], v[118:121], off
	global_store_dwordx4 v[224:225], v[114:117], off offset:16
	global_store_dwordx4 v[224:225], v[102:105], off offset:512
	global_store_dwordx4 v[224:225], v[98:101], off offset:528
	s_mov_b64 s[12:13], 0x120000
	v_lshl_add_u64 v[224:225], v[158:159], 0, s[12:13]
	global_load_dwordx4 v[228:231], v[224:225], off offset:16
	global_load_dwordx4 v[232:235], v[224:225], off offset:512
	global_load_dwordx4 v[236:239], v[224:225], off offset:528
	global_load_dwordx4 v[224:227], v[224:225], off
	s_waitcnt vmcnt(16)
;     __device__ __forceinline__ void operator()(const f32x4 (&acc)[2][2][4][2], const Unit& u, int wr, int wc, int fr, int fq, int lane) const {
;     ...
;             for (int m = 0; m < 4; ++m) { const size_t ro = (size_t)(row0 + ai * HALF + m * 16) * D + col0;
;                 f32x4 xo[2][2];
; #pragma unroll
;                 for (int bj = 0; bj < 2; ++bj)
; #pragma unroll
;                     for (int n = 0; n < 2; ++n) xo[bj][n] = *(const f32x4*)(xin + ro + bj * HALF + n * 4);
; #pragma unroll
;                 for (int bj = 0; bj < 2; ++bj)
; #pragma unroll
;                     for (int n = 0; n < 2; ++n) *(f32x4*)(out + ro + bj * HALF + n * 4) = xo[bj][n] + g[bj][n] * acc[ai][bj][m][n]; }
	v_pk_fma_f32 v[94:95], v[94:95], v[62:63], v[164:165]
	v_pk_fma_f32 v[96:97], v[96:97], v[64:65], v[166:167]
	v_pk_fma_f32 v[90:91], v[90:91], v[58:59], v[168:169]
	v_pk_fma_f32 v[92:93], v[92:93], v[60:61], v[170:171]
	v_pk_fma_f32 v[86:87], v[86:87], v[54:55], v[172:173]
	v_pk_fma_f32 v[88:89], v[88:89], v[56:57], v[174:175]
	v_pk_fma_f32 v[82:83], v[82:83], v[50:51], v[196:197]
	v_pk_fma_f32 v[84:85], v[84:85], v[52:53], v[198:199]
	s_mov_b64 s[12:13], 0x60000
	v_lshl_add_u64 v[164:165], v[158:159], 0, s[12:13]
	global_store_dwordx4 v[164:165], v[94:97], off
	global_store_dwordx4 v[164:165], v[90:93], off offset:16
	global_store_dwordx4 v[164:165], v[86:89], off offset:512
	global_store_dwordx4 v[164:165], v[82:85], off offset:528
	s_mov_b64 s[12:13], 0x140000
	v_lshl_add_u64 v[164:165], v[158:159], 0, s[12:13]
	global_load_dwordx4 v[168:171], v[164:165], off offset:16
	global_load_dwordx4 v[172:175], v[164:165], off offset:512
	global_load_dwordx4 v[196:199], v[164:165], off offset:528
	global_load_dwordx4 v[164:167], v[164:165], off
	s_waitcnt vmcnt(16)
	v_pk_fma_f32 v[78:79], v[78:79], v[62:63], v[200:201]
	v_pk_fma_f32 v[80:81], v[80:81], v[64:65], v[202:203]
	v_pk_fma_f32 v[74:75], v[74:75], v[58:59], v[204:205]
	v_pk_fma_f32 v[76:77], v[76:77], v[60:61], v[206:207]
	v_pk_fma_f32 v[70:71], v[70:71], v[54:55], v[208:209]
	v_pk_fma_f32 v[72:73], v[72:73], v[56:57], v[210:211]
	v_pk_fma_f32 v[66:67], v[66:67], v[50:51], v[212:213]
	v_pk_fma_f32 v[68:69], v[68:69], v[52:53], v[214:215]
	s_mov_b64 s[12:13], 0x100000
	v_lshl_add_u64 v[200:201], v[158:159], 0, s[12:13]
	global_store_dwordx4 v[200:201], v[78:81], off
	global_store_dwordx4 v[200:201], v[74:77], off offset:16
	global_store_dwordx4 v[200:201], v[70:73], off offset:512
	global_store_dwordx4 v[200:201], v[66:69], off offset:528
	s_mov_b64 s[12:13], 0x160000
	v_lshl_add_u64 v[200:201], v[158:159], 0, s[12:13]
	global_load_dwordx4 v[204:207], v[200:201], off offset:16
	global_load_dwordx4 v[208:211], v[200:201], off offset:512
	global_load_dwordx4 v[212:215], v[200:201], off offset:528
	global_load_dwordx4 v[200:203], v[200:201], off
	s_waitcnt vmcnt(16)
	v_pk_fma_f32 v[46:47], v[46:47], v[62:63], v[224:225]
	v_pk_fma_f32 v[48:49], v[48:49], v[64:65], v[226:227]
	v_pk_fma_f32 v[42:43], v[42:43], v[58:59], v[228:229]
	v_pk_fma_f32 v[44:45], v[44:45], v[60:61], v[230:231]
	v_pk_fma_f32 v[38:39], v[38:39], v[54:55], v[232:233]
	v_pk_fma_f32 v[40:41], v[40:41], v[56:57], v[234:235]
	v_pk_fma_f32 v[34:35], v[34:35], v[50:51], v[236:237]
	v_pk_fma_f32 v[36:37], v[36:37], v[52:53], v[238:239]
	s_mov_b64 s[12:13], 0x120000
	v_lshl_add_u64 v[224:225], v[158:159], 0, s[12:13]
	global_store_dwordx4 v[224:225], v[46:49], off
	global_store_dwordx4 v[224:225], v[42:45], off offset:16
	global_store_dwordx4 v[224:225], v[38:41], off offset:512
	global_store_dwordx4 v[224:225], v[34:37], off offset:528
	s_waitcnt vmcnt(12)
	v_pk_fma_f32 v[30:31], v[30:31], v[62:63], v[164:165]
	v_pk_fma_f32 v[32:33], v[32:33], v[64:65], v[166:167]
	v_pk_fma_f32 v[26:27], v[26:27], v[58:59], v[168:169]
	v_pk_fma_f32 v[28:29], v[28:29], v[60:61], v[170:171]
	v_pk_fma_f32 v[22:23], v[22:23], v[54:55], v[172:173]
	v_pk_fma_f32 v[24:25], v[24:25], v[56:57], v[174:175]
	v_pk_fma_f32 v[18:19], v[18:19], v[50:51], v[196:197]
	v_pk_fma_f32 v[20:21], v[20:21], v[52:53], v[198:199]
	s_mov_b64 s[12:13], 0x140000
	v_lshl_add_u64 v[164:165], v[158:159], 0, s[12:13]
	global_store_dwordx4 v[164:165], v[30:33], off
	global_store_dwordx4 v[164:165], v[26:29], off offset:16
	global_store_dwordx4 v[164:165], v[22:25], off offset:512
	global_store_dwordx4 v[164:165], v[18:21], off offset:528
	s_waitcnt vmcnt(8)
	v_pk_fma_f32 v[14:15], v[14:15], v[62:63], v[200:201]
	v_pk_fma_f32 v[16:17], v[16:17], v[64:65], v[202:203]
	v_pk_fma_f32 v[10:11], v[10:11], v[58:59], v[204:205]
	v_pk_fma_f32 v[12:13], v[12:13], v[60:61], v[206:207]
	v_pk_fma_f32 v[6:7], v[6:7], v[54:55], v[208:209]
	v_pk_fma_f32 v[8:9], v[8:9], v[56:57], v[210:211]
	v_pk_fma_f32 v[2:3], v[2:3], v[50:51], v[212:213]
	v_pk_fma_f32 v[4:5], v[4:5], v[52:53], v[214:215]
	s_mov_b64 s[12:13], 0x160000
	v_lshl_add_u64 v[200:201], v[158:159], 0, s[12:13]
	global_store_dwordx4 v[200:201], v[14:17], off
	global_store_dwordx4 v[200:201], v[10:13], off offset:16
	global_store_dwordx4 v[200:201], v[6:9], off offset:512
	global_store_dwordx4 v[200:201], v[2:5], off offset:528
	s_mov_b64 s[12:13], -1
	s_andn2_b64 vcc, exec, s[0:1]
	s_cbranch_vccnz .LBB0_347
	s_andn2_b64 vcc, exec, s[4:5]
	s_cbranch_vccnz .LBB0_346
	s_barrier
	s_branch .LBB0_346
